# v28: v27 + k-loop back edge rotated out of the first segment's head in both input-projection GEMMs (loop control + next-iteration pointer selects ahead of the loop-closing barrier, section 7.11) + lay
# baseline (speedup 1.0000x reference)
.LBB0_156:
	s_add_i32 s50, 16, 0x10000
	v_add_u32_e32 v151, s50, v176
	s_add_i32 s52, 16, 0x14000
	ds_read_b128 v[132:135], v151
	ds_read_b128 v[152:155], v151 offset:1024
	ds_read_b128 v[156:159], v151 offset:2048
	ds_read_b128 v[160:163], v151 offset:3072
	v_add_u32_e32 v151, s52, v176
	ds_read_b128 v[164:167], v151
	ds_read_b128 v[168:171], v151 offset:1024
	ds_read_b128 v[172:175], v151 offset:2048
	ds_read_b128 v[180:183], v151 offset:3072
	v_lshl_add_u64 v[216:217], s[0:1], 0, v[146:147]
	s_add_i32 m0, s37, 0xc000
	ds_read_b128 v[184:187], v178
	ds_read_b128 v[188:191], v178 offset:1024
	ds_read_b128 v[192:195], v178 offset:2048
	ds_read_b128 v[196:199], v178 offset:3072
	ds_read_b128 v[200:203], v178 offset:4096
	ds_read_b128 v[204:207], v178 offset:5120
	ds_read_b128 v[208:211], v178 offset:6144
	ds_read_b128 v[212:215], v178 offset:7168
	global_load_lds_dwordx4 v[216:217], off
	v_lshl_add_u64 v[216:217], s[0:1], 0, v[148:149]
	s_add_i32 m0, s37, 0xe000
	s_nop 0
	global_load_lds_dwordx4 v[216:217], off
	s_waitcnt vmcnt(8)
	s_waitcnt lgkmcnt(0)
	s_barrier
	s_setprio 1
	s_waitcnt lgkmcnt(0)
	v_mfma_f32_16x16x32_bf16 v[128:131], v[132:135], v[184:187], v[128:131]
	v_mfma_f32_16x16x32_bf16 v[124:127], v[156:159], v[184:187], v[124:127]
	v_mfma_f32_16x16x32_bf16 v[112:115], v[132:135], v[192:195], v[112:115]
	v_mfma_f32_16x16x32_bf16 v[108:111], v[156:159], v[192:195], v[108:111]
	v_mfma_f32_16x16x32_bf16 v[96:99], v[132:135], v[200:203], v[96:99]
	v_mfma_f32_16x16x32_bf16 v[92:95], v[156:159], v[200:203], v[92:95]
	v_mfma_f32_16x16x32_bf16 v[80:83], v[132:135], v[208:211], v[80:83]
	v_mfma_f32_16x16x32_bf16 v[76:79], v[156:159], v[208:211], v[76:79]
	v_mfma_f32_16x16x32_bf16 v[128:131], v[152:155], v[188:191], v[128:131]
	v_mfma_f32_16x16x32_bf16 v[124:127], v[160:163], v[188:191], v[124:127]
	v_mfma_f32_16x16x32_bf16 v[112:115], v[152:155], v[196:199], v[112:115]
	v_mfma_f32_16x16x32_bf16 v[108:111], v[160:163], v[196:199], v[108:111]
	v_mfma_f32_16x16x32_bf16 v[96:99], v[152:155], v[204:207], v[96:99]
	v_mfma_f32_16x16x32_bf16 v[92:95], v[160:163], v[204:207], v[92:95]
	v_mfma_f32_16x16x32_bf16 v[80:83], v[152:155], v[212:215], v[80:83]
	v_mfma_f32_16x16x32_bf16 v[76:79], v[160:163], v[212:215], v[76:79]
	s_setprio 0
	s_setprio 1
	v_mfma_f32_16x16x32_bf16 v[120:123], v[164:167], v[184:187], v[120:123]
	v_mfma_f32_16x16x32_bf16 v[116:119], v[172:175], v[184:187], v[116:119]
	v_mfma_f32_16x16x32_bf16 v[104:107], v[164:167], v[192:195], v[104:107]
	v_mfma_f32_16x16x32_bf16 v[100:103], v[172:175], v[192:195], v[100:103]
	v_mfma_f32_16x16x32_bf16 v[88:91], v[164:167], v[200:203], v[88:91]
	v_mfma_f32_16x16x32_bf16 v[84:87], v[172:175], v[200:203], v[84:87]
	v_mfma_f32_16x16x32_bf16 v[72:75], v[164:167], v[208:211], v[72:75]
	v_mfma_f32_16x16x32_bf16 v[68:71], v[172:175], v[208:211], v[68:71]
	v_mfma_f32_16x16x32_bf16 v[120:123], v[168:171], v[188:191], v[120:123]
	v_mfma_f32_16x16x32_bf16 v[116:119], v[180:183], v[188:191], v[116:119]
	v_mfma_f32_16x16x32_bf16 v[104:107], v[168:171], v[196:199], v[104:107]
	v_mfma_f32_16x16x32_bf16 v[100:103], v[180:183], v[196:199], v[100:103]
	v_mfma_f32_16x16x32_bf16 v[88:91], v[168:171], v[204:207], v[88:91]
	v_mfma_f32_16x16x32_bf16 v[84:87], v[180:183], v[204:207], v[84:87]
	v_mfma_f32_16x16x32_bf16 v[72:75], v[168:171], v[212:215], v[72:75]
	v_mfma_f32_16x16x32_bf16 v[68:71], v[180:183], v[212:215], v[68:71]
	s_setprio 0
	s_barrier
	s_add_i32 s50, s50, s36
	v_lshl_add_u64 v[216:217], s[6:7], 0, v[138:139]
	s_mov_b32 m0, s50
	ds_read_b128 v[184:187], v178 offset:16384
	ds_read_b128 v[188:191], v178 offset:17408
	ds_read_b128 v[192:195], v178 offset:18432
	ds_read_b128 v[196:199], v178 offset:19456
	ds_read_b128 v[200:203], v178 offset:20480
	ds_read_b128 v[204:207], v178 offset:21504
	ds_read_b128 v[208:211], v178 offset:22528
	ds_read_b128 v[212:215], v178 offset:23552
	global_load_lds_dwordx4 v[216:217], off
	s_add_i32 m0, s50, 0x2000
	s_add_u32 s50, s6, 0x40000
	v_lshl_add_u64 v[218:219], s[6:7], 0, v[0:1]
	s_addc_u32 s51, s7, 0
	s_add_i32 s52, s52, s36
	global_load_lds_dwordx4 v[218:219], off
	v_lshl_add_u64 v[220:221], s[50:51], 0, v[138:139]
	s_mov_b32 m0, s52
	v_lshl_add_u64 v[224:225], s[8:9], 0, v[136:137]
	global_load_lds_dwordx4 v[220:221], off
	v_lshl_add_u64 v[220:221], s[50:51], 0, v[0:1]
	s_add_i32 m0, s52, 0x2000
	s_nop 0
	global_load_lds_dwordx4 v[220:221], off
	v_lshl_add_u64 v[220:221], s[8:9], 0, v[140:141]
	s_waitcnt vmcnt(6)
	s_waitcnt lgkmcnt(0)
	s_barrier
	s_setprio 1
	s_waitcnt lgkmcnt(0)
	v_mfma_f32_16x16x32_bf16 v[64:67], v[132:135], v[184:187], v[64:67]
	v_mfma_f32_16x16x32_bf16 v[60:63], v[156:159], v[184:187], v[60:63]
	v_mfma_f32_16x16x32_bf16 v[48:51], v[132:135], v[192:195], v[48:51]
	v_mfma_f32_16x16x32_bf16 v[44:47], v[156:159], v[192:195], v[44:47]
	v_mfma_f32_16x16x32_bf16 v[32:35], v[132:135], v[200:203], v[32:35]
	v_mfma_f32_16x16x32_bf16 v[28:31], v[156:159], v[200:203], v[28:31]
	v_mfma_f32_16x16x32_bf16 v[16:19], v[132:135], v[208:211], v[16:19]
	v_mfma_f32_16x16x32_bf16 v[12:15], v[156:159], v[208:211], v[12:15]
	v_mfma_f32_16x16x32_bf16 v[64:67], v[152:155], v[188:191], v[64:67]
	v_mfma_f32_16x16x32_bf16 v[60:63], v[160:163], v[188:191], v[60:63]
	v_mfma_f32_16x16x32_bf16 v[48:51], v[152:155], v[196:199], v[48:51]
	v_mfma_f32_16x16x32_bf16 v[44:47], v[160:163], v[196:199], v[44:47]
	v_mfma_f32_16x16x32_bf16 v[32:35], v[152:155], v[204:207], v[32:35]
	v_mfma_f32_16x16x32_bf16 v[28:31], v[160:163], v[204:207], v[28:31]
	v_mfma_f32_16x16x32_bf16 v[16:19], v[152:155], v[212:215], v[16:19]
	v_mfma_f32_16x16x32_bf16 v[12:15], v[160:163], v[212:215], v[12:15]
	s_setprio 0
	s_setprio 1
	v_mfma_f32_16x16x32_bf16 v[56:59], v[164:167], v[184:187], v[56:59]
	v_mfma_f32_16x16x32_bf16 v[52:55], v[172:175], v[184:187], v[52:55]
	v_mfma_f32_16x16x32_bf16 v[40:43], v[164:167], v[192:195], v[40:43]
	v_mfma_f32_16x16x32_bf16 v[36:39], v[172:175], v[192:195], v[36:39]
	v_mfma_f32_16x16x32_bf16 v[24:27], v[164:167], v[200:203], v[24:27]
	v_mfma_f32_16x16x32_bf16 v[20:23], v[172:175], v[200:203], v[20:23]
	v_mfma_f32_16x16x32_bf16 v[8:11], v[164:167], v[208:211], v[8:11]
	v_mfma_f32_16x16x32_bf16 v[4:7], v[172:175], v[208:211], v[4:7]
	v_mfma_f32_16x16x32_bf16 v[56:59], v[168:171], v[188:191], v[56:59]
	v_mfma_f32_16x16x32_bf16 v[52:55], v[180:183], v[188:191], v[52:55]
	v_mfma_f32_16x16x32_bf16 v[40:43], v[168:171], v[196:199], v[40:43]
	v_mfma_f32_16x16x32_bf16 v[36:39], v[180:183], v[196:199], v[36:39]
	v_mfma_f32_16x16x32_bf16 v[24:27], v[168:171], v[204:207], v[24:27]
	v_mfma_f32_16x16x32_bf16 v[20:23], v[180:183], v[204:207], v[20:23]
	v_mfma_f32_16x16x32_bf16 v[8:11], v[168:171], v[212:215], v[8:11]
	v_mfma_f32_16x16x32_bf16 v[4:7], v[180:183], v[212:215], v[4:7]
	s_setprio 0
	s_barrier
.Lb1_ph3:
	s_add_i32 s50, 16, 0x18000
	v_add_u32_e32 v151, s50, v176
	s_add_i32 s51, 16, 0x1c000
	ds_read_b128 v[132:135], v151
	ds_read_b128 v[152:155], v151 offset:1024
	ds_read_b128 v[156:159], v151 offset:2048
	ds_read_b128 v[160:163], v151 offset:3072
	v_add_u32_e32 v151, s51, v176
	ds_read_b128 v[164:167], v151
	ds_read_b128 v[168:171], v151 offset:1024
	ds_read_b128 v[172:175], v151 offset:2048
	ds_read_b128 v[180:183], v151 offset:3072
	s_mov_b32 m0, s37
	s_nop 0
	global_load_lds_dwordx4 v[220:221], off
	s_mov_b32 m0, s38
	s_nop 0
	global_load_lds_dwordx4 v[224:225], off
	s_add_u32 s8, s8, 0x40000
	s_addc_u32 s9, s9, 0
	s_mov_b32 m0, s39
	v_lshl_add_u64 v[226:227], s[8:9], 0, v[140:141]
	ds_read_b128 v[184:187], v178 offset:32768
	ds_read_b128 v[188:191], v178 offset:33792
	ds_read_b128 v[192:195], v178 offset:34816
	ds_read_b128 v[196:199], v178 offset:35840
	ds_read_b128 v[200:203], v178 offset:36864
	ds_read_b128 v[204:207], v178 offset:37888
	ds_read_b128 v[208:211], v178 offset:38912
	ds_read_b128 v[212:215], v178 offset:39936
	global_load_lds_dwordx4 v[226:227], off
	v_lshl_add_u64 v[226:227], s[8:9], 0, v[136:137]
	s_mov_b32 m0, s40
	s_nop 0
	global_load_lds_dwordx4 v[226:227], off
	s_waitcnt vmcnt(8)
	s_waitcnt lgkmcnt(0)
	s_barrier
	s_setprio 1
	s_waitcnt lgkmcnt(0)
	v_mfma_f32_16x16x32_bf16 v[128:131], v[132:135], v[184:187], v[128:131]
	v_mfma_f32_16x16x32_bf16 v[124:127], v[156:159], v[184:187], v[124:127]
	v_mfma_f32_16x16x32_bf16 v[112:115], v[132:135], v[192:195], v[112:115]
	v_mfma_f32_16x16x32_bf16 v[108:111], v[156:159], v[192:195], v[108:111]
	v_mfma_f32_16x16x32_bf16 v[96:99], v[132:135], v[200:203], v[96:99]
	v_mfma_f32_16x16x32_bf16 v[92:95], v[156:159], v[200:203], v[92:95]
	v_mfma_f32_16x16x32_bf16 v[80:83], v[132:135], v[208:211], v[80:83]
	v_mfma_f32_16x16x32_bf16 v[76:79], v[156:159], v[208:211], v[76:79]
	v_mfma_f32_16x16x32_bf16 v[128:131], v[152:155], v[188:191], v[128:131]
	v_mfma_f32_16x16x32_bf16 v[124:127], v[160:163], v[188:191], v[124:127]
	v_mfma_f32_16x16x32_bf16 v[112:115], v[152:155], v[196:199], v[112:115]
	v_mfma_f32_16x16x32_bf16 v[108:111], v[160:163], v[196:199], v[108:111]
	v_mfma_f32_16x16x32_bf16 v[96:99], v[152:155], v[204:207], v[96:99]
	v_mfma_f32_16x16x32_bf16 v[92:95], v[160:163], v[204:207], v[92:95]
	v_mfma_f32_16x16x32_bf16 v[80:83], v[152:155], v[212:215], v[80:83]
	v_mfma_f32_16x16x32_bf16 v[76:79], v[160:163], v[212:215], v[76:79]
	s_setprio 0
	s_setprio 1
	v_mfma_f32_16x16x32_bf16 v[120:123], v[164:167], v[184:187], v[120:123]
	v_mfma_f32_16x16x32_bf16 v[116:119], v[172:175], v[184:187], v[116:119]
	v_mfma_f32_16x16x32_bf16 v[104:107], v[164:167], v[192:195], v[104:107]
	v_mfma_f32_16x16x32_bf16 v[100:103], v[172:175], v[192:195], v[100:103]
	v_mfma_f32_16x16x32_bf16 v[88:91], v[164:167], v[200:203], v[88:91]
	v_mfma_f32_16x16x32_bf16 v[84:87], v[172:175], v[200:203], v[84:87]
	v_mfma_f32_16x16x32_bf16 v[72:75], v[164:167], v[208:211], v[72:75]
	v_mfma_f32_16x16x32_bf16 v[68:71], v[172:175], v[208:211], v[68:71]
	v_mfma_f32_16x16x32_bf16 v[120:123], v[168:171], v[188:191], v[120:123]
	v_mfma_f32_16x16x32_bf16 v[116:119], v[180:183], v[188:191], v[116:119]
	v_mfma_f32_16x16x32_bf16 v[104:107], v[168:171], v[196:199], v[104:107]
	v_mfma_f32_16x16x32_bf16 v[100:103], v[180:183], v[196:199], v[100:103]
	v_mfma_f32_16x16x32_bf16 v[88:91], v[168:171], v[204:207], v[88:91]
	v_mfma_f32_16x16x32_bf16 v[84:87], v[180:183], v[204:207], v[84:87]
	v_mfma_f32_16x16x32_bf16 v[72:75], v[168:171], v[212:215], v[72:75]
	v_mfma_f32_16x16x32_bf16 v[68:71], v[180:183], v[212:215], v[68:71]
	s_setprio 0
	s_barrier
	s_add_i32 s8, s50, s36
	v_lshl_add_u64 v[216:217], v[216:217], 0, s[84:85]
	s_mov_b32 m0, s8
	ds_read_b128 v[184:187], v178 offset:49152
	ds_read_b128 v[188:191], v178 offset:50176
	ds_read_b128 v[192:195], v178 offset:51200
	ds_read_b128 v[196:199], v178 offset:52224
	ds_read_b128 v[200:203], v178 offset:53248
	ds_read_b128 v[204:207], v178 offset:54272
	ds_read_b128 v[208:211], v178 offset:55296
	ds_read_b128 v[212:215], v178 offset:56320
	global_load_lds_dwordx4 v[216:217], off
	s_add_i32 m0, s8, 0x2000
	s_add_u32 s6, s6, 0x40080
	v_lshl_add_u64 v[216:217], v[218:219], 0, s[84:85]
	s_addc_u32 s7, s7, 0
	s_add_i32 s8, s51, s36
	global_load_lds_dwordx4 v[216:217], off
	v_lshl_add_u64 v[216:217], s[6:7], 0, v[138:139]
	s_mov_b32 m0, s8
	s_nop 0
	global_load_lds_dwordx4 v[216:217], off
	v_lshl_add_u64 v[216:217], s[6:7], 0, v[0:1]
	s_add_i32 m0, s8, 0x2000
	s_nop 0
	global_load_lds_dwordx4 v[216:217], off
	v_lshl_add_u64 v[216:217], v[220:221], 0, s[84:85]
	s_mov_b32 m0, s44
	s_nop 0
	global_load_lds_dwordx4 v[216:217], off
	v_lshl_add_u64 v[216:217], v[224:225], 0, s[84:85]
	s_mov_b32 m0, s45
	s_nop 0
	global_load_lds_dwordx4 v[216:217], off
	s_waitcnt vmcnt(8)
	s_waitcnt lgkmcnt(0)
	s_barrier
	s_setprio 1
	s_waitcnt lgkmcnt(0)
	v_mfma_f32_16x16x32_bf16 v[64:67], v[132:135], v[184:187], v[64:67]
	v_mfma_f32_16x16x32_bf16 v[60:63], v[156:159], v[184:187], v[60:63]
	v_mfma_f32_16x16x32_bf16 v[48:51], v[132:135], v[192:195], v[48:51]
	v_mfma_f32_16x16x32_bf16 v[44:47], v[156:159], v[192:195], v[44:47]
	v_mfma_f32_16x16x32_bf16 v[32:35], v[132:135], v[200:203], v[32:35]
	v_mfma_f32_16x16x32_bf16 v[28:31], v[156:159], v[200:203], v[28:31]
	v_mfma_f32_16x16x32_bf16 v[16:19], v[132:135], v[208:211], v[16:19]
	v_mfma_f32_16x16x32_bf16 v[12:15], v[156:159], v[208:211], v[12:15]
	v_mfma_f32_16x16x32_bf16 v[64:67], v[152:155], v[188:191], v[64:67]
	v_mfma_f32_16x16x32_bf16 v[60:63], v[160:163], v[188:191], v[60:63]
	v_mfma_f32_16x16x32_bf16 v[48:51], v[152:155], v[196:199], v[48:51]
	v_mfma_f32_16x16x32_bf16 v[44:47], v[160:163], v[196:199], v[44:47]
	v_mfma_f32_16x16x32_bf16 v[32:35], v[152:155], v[204:207], v[32:35]
	v_mfma_f32_16x16x32_bf16 v[28:31], v[160:163], v[204:207], v[28:31]
	v_mfma_f32_16x16x32_bf16 v[16:19], v[152:155], v[212:215], v[16:19]
	v_mfma_f32_16x16x32_bf16 v[12:15], v[160:163], v[212:215], v[12:15]
	s_setprio 0
	s_setprio 1
	v_mfma_f32_16x16x32_bf16 v[56:59], v[164:167], v[184:187], v[56:59]
	v_mfma_f32_16x16x32_bf16 v[52:55], v[172:175], v[184:187], v[52:55]
	v_mfma_f32_16x16x32_bf16 v[40:43], v[164:167], v[192:195], v[40:43]
	v_mfma_f32_16x16x32_bf16 v[36:39], v[172:175], v[192:195], v[36:39]
	v_mfma_f32_16x16x32_bf16 v[24:27], v[164:167], v[200:203], v[24:27]
	v_mfma_f32_16x16x32_bf16 v[20:23], v[172:175], v[200:203], v[20:23]
	v_mfma_f32_16x16x32_bf16 v[8:11], v[164:167], v[208:211], v[8:11]
	v_mfma_f32_16x16x32_bf16 v[4:7], v[172:175], v[208:211], v[4:7]
	v_mfma_f32_16x16x32_bf16 v[56:59], v[168:171], v[188:191], v[56:59]
	v_mfma_f32_16x16x32_bf16 v[52:55], v[180:183], v[188:191], v[52:55]
	v_mfma_f32_16x16x32_bf16 v[40:43], v[168:171], v[196:199], v[40:43]
	v_mfma_f32_16x16x32_bf16 v[36:39], v[180:183], v[196:199], v[36:39]
	v_mfma_f32_16x16x32_bf16 v[24:27], v[168:171], v[204:207], v[24:27]
	v_mfma_f32_16x16x32_bf16 v[20:23], v[180:183], v[204:207], v[20:23]
	v_mfma_f32_16x16x32_bf16 v[8:11], v[168:171], v[212:215], v[8:11]
	v_mfma_f32_16x16x32_bf16 v[4:7], v[180:183], v[212:215], v[4:7]
	s_setprio 0
	s_add_i32 s49, s49, 2
	s_add_u32 s0, s0, 0x100
	s_addc_u32 s1, s1, 0
	s_add_u32 s29, s29, 0x100
	s_addc_u32 s42, s42, 0
	s_add_u32 s6, s0, 0xfffc0080
	s_addc_u32 s7, s1, -1
	s_cmp_eq_u32 s49, 12
	s_cselect_b32 s9, s3, s7
	s_cselect_b32 s8, s23, s6
	s_cselect_b32 s7, s21, s42
	s_cselect_b32 s6, s28, s29
	s_barrier
	s_cmp_gt_u32 s49, 13
	s_cbranch_scc0 .LBB0_156
	s_and_b64 vcc, exec, s[18:19]
	s_cbranch_vccz .LBB0_159
	s_barrier

.LBB0_445:
	s_ashr_i32 s23, s22, 31
	s_lshl_b64 s[24:25], s[22:23], 19
	s_add_u32 s24, s34, s24
	s_addc_u32 s25, s35, s25
	s_and_b64 s[26:27], s[6:7], exec
	s_cselect_b32 s3, s25, s1
	s_cselect_b32 s23, s24, s0
	s_ashr_i32 s21, s20, 31
	s_lshl_b64 s[26:27], s[20:21], 19
	s_add_u32 s26, s36, s26
	s_addc_u32 s27, s37, s27
	s_and_b64 s[30:31], s[6:7], exec
	s_cselect_b32 s21, s27, s29
	s_cselect_b32 s48, s26, s28
	s_add_u32 s0, s0, 0x40080
	s_addc_u32 s1, s1, 0
	s_add_u32 s49, s28, 0x100
	s_addc_u32 s50, s29, 0
	s_mov_b32 s51, -2
	s_waitcnt vmcnt(0)
	s_add_u32 s28, s0, 0xfffc0080
	s_addc_u32 s29, s1, -1
	s_add_i32 s52, 16, 0x10000
	s_cmp_eq_u32 s51, 12
	s_cselect_b32 s31, s3, s29
	s_cselect_b32 s30, s23, s28
	v_add_u32_e32 v3, s52, v175
	s_cselect_b32 s29, s21, s50
	s_cselect_b32 s28, s48, s49
	s_add_i32 s54, 16, 0x14000
	ds_read_b128 v[142:145], v3
	ds_read_b128 v[146:149], v3 offset:1024
	ds_read_b128 v[150:153], v3 offset:2048
	ds_read_b128 v[154:157], v3 offset:3072
	v_add_u32_e32 v3, s54, v175
	ds_read_b128 v[158:161], v3
	ds_read_b128 v[162:165], v3 offset:1024
	ds_read_b128 v[166:169], v3 offset:2048
	ds_read_b128 v[170:173], v3 offset:3072
	v_lshl_add_u64 v[210:211], s[0:1], 0, v[138:139]
	s_add_i32 m0, s39, 0xc000
	ds_read_b128 v[178:181], v177
	ds_read_b128 v[182:185], v177 offset:1024
	ds_read_b128 v[186:189], v177 offset:2048
	ds_read_b128 v[190:193], v177 offset:3072
	ds_read_b128 v[194:197], v177 offset:4096
	ds_read_b128 v[198:201], v177 offset:5120
	ds_read_b128 v[202:205], v177 offset:6144
	ds_read_b128 v[206:209], v177 offset:7168
	global_load_lds_dwordx4 v[210:211], off
	v_lshl_add_u64 v[210:211], s[0:1], 0, v[140:141]
	s_add_i32 m0, s39, 0xe000
	s_nop 0
	global_load_lds_dwordx4 v[210:211], off
	s_waitcnt vmcnt(8)
	s_waitcnt lgkmcnt(0)
	s_barrier
	s_setprio 1
	s_waitcnt lgkmcnt(0)
	v_mfma_f32_16x16x32_bf16 v[128:131], v[142:145], v[178:181], 0
	v_mfma_f32_16x16x32_bf16 v[120:123], v[150:153], v[178:181], 0
	v_mfma_f32_16x16x32_bf16 v[112:115], v[142:145], v[186:189], 0
	v_mfma_f32_16x16x32_bf16 v[104:107], v[150:153], v[186:189], 0
	v_mfma_f32_16x16x32_bf16 v[96:99], v[142:145], v[194:197], 0
	v_mfma_f32_16x16x32_bf16 v[88:91], v[150:153], v[194:197], 0
	v_mfma_f32_16x16x32_bf16 v[80:83], v[142:145], v[202:205], 0
	v_mfma_f32_16x16x32_bf16 v[72:75], v[150:153], v[202:205], 0
	v_mfma_f32_16x16x32_bf16 v[128:131], v[146:149], v[182:185], v[128:131]
	v_mfma_f32_16x16x32_bf16 v[120:123], v[154:157], v[182:185], v[120:123]
	v_mfma_f32_16x16x32_bf16 v[112:115], v[146:149], v[190:193], v[112:115]
	v_mfma_f32_16x16x32_bf16 v[104:107], v[154:157], v[190:193], v[104:107]
	v_mfma_f32_16x16x32_bf16 v[96:99], v[146:149], v[198:201], v[96:99]
	v_mfma_f32_16x16x32_bf16 v[88:91], v[154:157], v[198:201], v[88:91]
	v_mfma_f32_16x16x32_bf16 v[80:83], v[146:149], v[206:209], v[80:83]
	v_mfma_f32_16x16x32_bf16 v[72:75], v[154:157], v[206:209], v[72:75]
	s_setprio 0
	s_setprio 1
	v_mfma_f32_16x16x32_bf16 v[124:127], v[158:161], v[178:181], 0
	v_mfma_f32_16x16x32_bf16 v[116:119], v[166:169], v[178:181], 0
	v_mfma_f32_16x16x32_bf16 v[108:111], v[158:161], v[186:189], 0
	v_mfma_f32_16x16x32_bf16 v[100:103], v[166:169], v[186:189], 0
	v_mfma_f32_16x16x32_bf16 v[92:95], v[158:161], v[194:197], 0
	v_mfma_f32_16x16x32_bf16 v[84:87], v[166:169], v[194:197], 0
	v_mfma_f32_16x16x32_bf16 v[76:79], v[158:161], v[202:205], 0
	v_mfma_f32_16x16x32_bf16 v[68:71], v[166:169], v[202:205], 0
	v_mfma_f32_16x16x32_bf16 v[124:127], v[162:165], v[182:185], v[124:127]
	v_mfma_f32_16x16x32_bf16 v[116:119], v[170:173], v[182:185], v[116:119]
	v_mfma_f32_16x16x32_bf16 v[108:111], v[162:165], v[190:193], v[108:111]
	v_mfma_f32_16x16x32_bf16 v[100:103], v[170:173], v[190:193], v[100:103]
	v_mfma_f32_16x16x32_bf16 v[92:95], v[162:165], v[198:201], v[92:95]
	v_mfma_f32_16x16x32_bf16 v[84:87], v[170:173], v[198:201], v[84:87]
	v_mfma_f32_16x16x32_bf16 v[76:79], v[162:165], v[206:209], v[76:79]
	v_mfma_f32_16x16x32_bf16 v[68:71], v[170:173], v[206:209], v[68:71]
	s_setprio 0
	s_barrier
	s_add_i32 s52, s52, s38
	v_lshl_add_u64 v[210:211], s[28:29], 0, v[134:135]
	s_mov_b32 m0, s52
	ds_read_b128 v[178:181], v177 offset:16384
	ds_read_b128 v[182:185], v177 offset:17408
	ds_read_b128 v[186:189], v177 offset:18432
	ds_read_b128 v[190:193], v177 offset:19456
	ds_read_b128 v[194:197], v177 offset:20480
	ds_read_b128 v[198:201], v177 offset:21504
	ds_read_b128 v[202:205], v177 offset:22528
	ds_read_b128 v[206:209], v177 offset:23552
	global_load_lds_dwordx4 v[210:211], off
	s_add_i32 m0, s52, 0x2000
	s_add_u32 s52, s28, 0x40000
	v_lshl_add_u64 v[212:213], s[28:29], 0, v[0:1]
	s_addc_u32 s53, s29, 0
	s_add_i32 s54, s54, s38
	global_load_lds_dwordx4 v[212:213], off
	v_lshl_add_u64 v[214:215], s[52:53], 0, v[134:135]
	s_mov_b32 m0, s54
	v_lshl_add_u64 v[216:217], s[30:31], 0, v[132:133]
	global_load_lds_dwordx4 v[214:215], off
	v_lshl_add_u64 v[214:215], s[52:53], 0, v[0:1]
	s_add_i32 m0, s54, 0x2000
	s_nop 0
	global_load_lds_dwordx4 v[214:215], off
	v_lshl_add_u64 v[214:215], s[30:31], 0, v[136:137]
	s_waitcnt vmcnt(6)
	s_waitcnt lgkmcnt(0)
	s_barrier
	s_setprio 1
	s_waitcnt lgkmcnt(0)
	v_mfma_f32_16x16x32_bf16 v[64:67], v[142:145], v[178:181], 0
	v_mfma_f32_16x16x32_bf16 v[56:59], v[150:153], v[178:181], 0
	v_mfma_f32_16x16x32_bf16 v[48:51], v[142:145], v[186:189], 0
	v_mfma_f32_16x16x32_bf16 v[40:43], v[150:153], v[186:189], 0
	v_mfma_f32_16x16x32_bf16 v[32:35], v[142:145], v[194:197], 0
	v_mfma_f32_16x16x32_bf16 v[24:27], v[150:153], v[194:197], 0
	v_mfma_f32_16x16x32_bf16 v[16:19], v[142:145], v[202:205], 0
	v_mfma_f32_16x16x32_bf16 v[8:11], v[150:153], v[202:205], 0
	v_mfma_f32_16x16x32_bf16 v[64:67], v[146:149], v[182:185], v[64:67]
	v_mfma_f32_16x16x32_bf16 v[56:59], v[154:157], v[182:185], v[56:59]
	v_mfma_f32_16x16x32_bf16 v[48:51], v[146:149], v[190:193], v[48:51]
	v_mfma_f32_16x16x32_bf16 v[40:43], v[154:157], v[190:193], v[40:43]
	v_mfma_f32_16x16x32_bf16 v[32:35], v[146:149], v[198:201], v[32:35]
	v_mfma_f32_16x16x32_bf16 v[24:27], v[154:157], v[198:201], v[24:27]
	v_mfma_f32_16x16x32_bf16 v[16:19], v[146:149], v[206:209], v[16:19]
	v_mfma_f32_16x16x32_bf16 v[8:11], v[154:157], v[206:209], v[8:11]
	s_setprio 0
	s_setprio 1
	v_mfma_f32_16x16x32_bf16 v[60:63], v[158:161], v[178:181], 0
	v_mfma_f32_16x16x32_bf16 v[52:55], v[166:169], v[178:181], 0
	v_mfma_f32_16x16x32_bf16 v[44:47], v[158:161], v[186:189], 0
	v_mfma_f32_16x16x32_bf16 v[36:39], v[166:169], v[186:189], 0
	v_mfma_f32_16x16x32_bf16 v[28:31], v[158:161], v[194:197], 0
	v_mfma_f32_16x16x32_bf16 v[20:23], v[166:169], v[194:197], 0
	v_mfma_f32_16x16x32_bf16 v[12:15], v[158:161], v[202:205], 0
	v_mfma_f32_16x16x32_bf16 v[4:7], v[166:169], v[202:205], 0
	v_mfma_f32_16x16x32_bf16 v[60:63], v[162:165], v[182:185], v[60:63]
	v_mfma_f32_16x16x32_bf16 v[52:55], v[170:173], v[182:185], v[52:55]
	v_mfma_f32_16x16x32_bf16 v[44:47], v[162:165], v[190:193], v[44:47]
	v_mfma_f32_16x16x32_bf16 v[36:39], v[170:173], v[190:193], v[36:39]
	v_mfma_f32_16x16x32_bf16 v[28:31], v[162:165], v[198:201], v[28:31]
	v_mfma_f32_16x16x32_bf16 v[20:23], v[170:173], v[198:201], v[20:23]
	v_mfma_f32_16x16x32_bf16 v[12:15], v[162:165], v[206:209], v[12:15]
	v_mfma_f32_16x16x32_bf16 v[4:7], v[170:173], v[206:209], v[4:7]
	s_setprio 0
	s_barrier
	s_branch .La1_ph3
.LBB0_446:
	s_add_i32 s52, 16, 0x10000
	v_add_u32_e32 v3, s52, v175
	s_add_i32 s54, 16, 0x14000
	ds_read_b128 v[142:145], v3
	ds_read_b128 v[146:149], v3 offset:1024
	ds_read_b128 v[150:153], v3 offset:2048
	ds_read_b128 v[154:157], v3 offset:3072
	v_add_u32_e32 v3, s54, v175
	ds_read_b128 v[158:161], v3
	ds_read_b128 v[162:165], v3 offset:1024
	ds_read_b128 v[166:169], v3 offset:2048
	ds_read_b128 v[170:173], v3 offset:3072
	v_lshl_add_u64 v[210:211], s[0:1], 0, v[138:139]
	s_add_i32 m0, s39, 0xc000
	ds_read_b128 v[178:181], v177
	ds_read_b128 v[182:185], v177 offset:1024
	ds_read_b128 v[186:189], v177 offset:2048
	ds_read_b128 v[190:193], v177 offset:3072
	ds_read_b128 v[194:197], v177 offset:4096
	ds_read_b128 v[198:201], v177 offset:5120
	ds_read_b128 v[202:205], v177 offset:6144
	ds_read_b128 v[206:209], v177 offset:7168
	global_load_lds_dwordx4 v[210:211], off
	v_lshl_add_u64 v[210:211], s[0:1], 0, v[140:141]
	s_add_i32 m0, s39, 0xe000
	s_nop 0
	global_load_lds_dwordx4 v[210:211], off
	s_waitcnt vmcnt(8)
	s_waitcnt lgkmcnt(0)
	s_barrier
	s_setprio 1
	s_waitcnt lgkmcnt(0)
	v_mfma_f32_16x16x32_bf16 v[128:131], v[142:145], v[178:181], v[128:131]
	v_mfma_f32_16x16x32_bf16 v[120:123], v[150:153], v[178:181], v[120:123]
	v_mfma_f32_16x16x32_bf16 v[112:115], v[142:145], v[186:189], v[112:115]
	v_mfma_f32_16x16x32_bf16 v[104:107], v[150:153], v[186:189], v[104:107]
	v_mfma_f32_16x16x32_bf16 v[96:99], v[142:145], v[194:197], v[96:99]
	v_mfma_f32_16x16x32_bf16 v[88:91], v[150:153], v[194:197], v[88:91]
	v_mfma_f32_16x16x32_bf16 v[80:83], v[142:145], v[202:205], v[80:83]
	v_mfma_f32_16x16x32_bf16 v[72:75], v[150:153], v[202:205], v[72:75]
	v_mfma_f32_16x16x32_bf16 v[128:131], v[146:149], v[182:185], v[128:131]
	v_mfma_f32_16x16x32_bf16 v[120:123], v[154:157], v[182:185], v[120:123]
	v_mfma_f32_16x16x32_bf16 v[112:115], v[146:149], v[190:193], v[112:115]
	v_mfma_f32_16x16x32_bf16 v[104:107], v[154:157], v[190:193], v[104:107]
	v_mfma_f32_16x16x32_bf16 v[96:99], v[146:149], v[198:201], v[96:99]
	v_mfma_f32_16x16x32_bf16 v[88:91], v[154:157], v[198:201], v[88:91]
	v_mfma_f32_16x16x32_bf16 v[80:83], v[146:149], v[206:209], v[80:83]
	v_mfma_f32_16x16x32_bf16 v[72:75], v[154:157], v[206:209], v[72:75]
	s_setprio 0
	s_setprio 1
	v_mfma_f32_16x16x32_bf16 v[124:127], v[158:161], v[178:181], v[124:127]
	v_mfma_f32_16x16x32_bf16 v[116:119], v[166:169], v[178:181], v[116:119]
	v_mfma_f32_16x16x32_bf16 v[108:111], v[158:161], v[186:189], v[108:111]
	v_mfma_f32_16x16x32_bf16 v[100:103], v[166:169], v[186:189], v[100:103]
	v_mfma_f32_16x16x32_bf16 v[92:95], v[158:161], v[194:197], v[92:95]
	v_mfma_f32_16x16x32_bf16 v[84:87], v[166:169], v[194:197], v[84:87]
	v_mfma_f32_16x16x32_bf16 v[76:79], v[158:161], v[202:205], v[76:79]
	v_mfma_f32_16x16x32_bf16 v[68:71], v[166:169], v[202:205], v[68:71]
	v_mfma_f32_16x16x32_bf16 v[124:127], v[162:165], v[182:185], v[124:127]
	v_mfma_f32_16x16x32_bf16 v[116:119], v[170:173], v[182:185], v[116:119]
	v_mfma_f32_16x16x32_bf16 v[108:111], v[162:165], v[190:193], v[108:111]
	v_mfma_f32_16x16x32_bf16 v[100:103], v[170:173], v[190:193], v[100:103]
	v_mfma_f32_16x16x32_bf16 v[92:95], v[162:165], v[198:201], v[92:95]
	v_mfma_f32_16x16x32_bf16 v[84:87], v[170:173], v[198:201], v[84:87]
	v_mfma_f32_16x16x32_bf16 v[76:79], v[162:165], v[206:209], v[76:79]
	v_mfma_f32_16x16x32_bf16 v[68:71], v[170:173], v[206:209], v[68:71]
	s_setprio 0
	s_barrier
	s_add_i32 s52, s52, s38
	v_lshl_add_u64 v[210:211], s[28:29], 0, v[134:135]
	s_mov_b32 m0, s52
	ds_read_b128 v[178:181], v177 offset:16384
	ds_read_b128 v[182:185], v177 offset:17408
	ds_read_b128 v[186:189], v177 offset:18432
	ds_read_b128 v[190:193], v177 offset:19456
	ds_read_b128 v[194:197], v177 offset:20480
	ds_read_b128 v[198:201], v177 offset:21504
	ds_read_b128 v[202:205], v177 offset:22528
	ds_read_b128 v[206:209], v177 offset:23552
	global_load_lds_dwordx4 v[210:211], off
	s_add_i32 m0, s52, 0x2000
	s_add_u32 s52, s28, 0x40000
	v_lshl_add_u64 v[212:213], s[28:29], 0, v[0:1]
	s_addc_u32 s53, s29, 0
	s_add_i32 s54, s54, s38
	global_load_lds_dwordx4 v[212:213], off
	v_lshl_add_u64 v[214:215], s[52:53], 0, v[134:135]
	s_mov_b32 m0, s54
	v_lshl_add_u64 v[216:217], s[30:31], 0, v[132:133]
	global_load_lds_dwordx4 v[214:215], off
	v_lshl_add_u64 v[214:215], s[52:53], 0, v[0:1]
	s_add_i32 m0, s54, 0x2000
	s_nop 0
	global_load_lds_dwordx4 v[214:215], off
	v_lshl_add_u64 v[214:215], s[30:31], 0, v[136:137]
	s_waitcnt vmcnt(6)
	s_waitcnt lgkmcnt(0)
	s_barrier
	s_setprio 1
	s_waitcnt lgkmcnt(0)
	v_mfma_f32_16x16x32_bf16 v[64:67], v[142:145], v[178:181], v[64:67]
	v_mfma_f32_16x16x32_bf16 v[56:59], v[150:153], v[178:181], v[56:59]
	v_mfma_f32_16x16x32_bf16 v[48:51], v[142:145], v[186:189], v[48:51]
	v_mfma_f32_16x16x32_bf16 v[40:43], v[150:153], v[186:189], v[40:43]
	v_mfma_f32_16x16x32_bf16 v[32:35], v[142:145], v[194:197], v[32:35]
	v_mfma_f32_16x16x32_bf16 v[24:27], v[150:153], v[194:197], v[24:27]
	v_mfma_f32_16x16x32_bf16 v[16:19], v[142:145], v[202:205], v[16:19]
	v_mfma_f32_16x16x32_bf16 v[8:11], v[150:153], v[202:205], v[8:11]
	v_mfma_f32_16x16x32_bf16 v[64:67], v[146:149], v[182:185], v[64:67]
	v_mfma_f32_16x16x32_bf16 v[56:59], v[154:157], v[182:185], v[56:59]
	v_mfma_f32_16x16x32_bf16 v[48:51], v[146:149], v[190:193], v[48:51]
	v_mfma_f32_16x16x32_bf16 v[40:43], v[154:157], v[190:193], v[40:43]
	v_mfma_f32_16x16x32_bf16 v[32:35], v[146:149], v[198:201], v[32:35]
	v_mfma_f32_16x16x32_bf16 v[24:27], v[154:157], v[198:201], v[24:27]
	v_mfma_f32_16x16x32_bf16 v[16:19], v[146:149], v[206:209], v[16:19]
	v_mfma_f32_16x16x32_bf16 v[8:11], v[154:157], v[206:209], v[8:11]
	s_setprio 0
	s_setprio 1
	v_mfma_f32_16x16x32_bf16 v[60:63], v[158:161], v[178:181], v[60:63]
	v_mfma_f32_16x16x32_bf16 v[52:55], v[166:169], v[178:181], v[52:55]
	v_mfma_f32_16x16x32_bf16 v[44:47], v[158:161], v[186:189], v[44:47]
	v_mfma_f32_16x16x32_bf16 v[36:39], v[166:169], v[186:189], v[36:39]
	v_mfma_f32_16x16x32_bf16 v[28:31], v[158:161], v[194:197], v[28:31]
	v_mfma_f32_16x16x32_bf16 v[20:23], v[166:169], v[194:197], v[20:23]
	v_mfma_f32_16x16x32_bf16 v[12:15], v[158:161], v[202:205], v[12:15]
	v_mfma_f32_16x16x32_bf16 v[4:7], v[166:169], v[202:205], v[4:7]
	v_mfma_f32_16x16x32_bf16 v[60:63], v[162:165], v[182:185], v[60:63]
	v_mfma_f32_16x16x32_bf16 v[52:55], v[170:173], v[182:185], v[52:55]
	v_mfma_f32_16x16x32_bf16 v[44:47], v[162:165], v[190:193], v[44:47]
	v_mfma_f32_16x16x32_bf16 v[36:39], v[170:173], v[190:193], v[36:39]
	v_mfma_f32_16x16x32_bf16 v[28:31], v[162:165], v[198:201], v[28:31]
	v_mfma_f32_16x16x32_bf16 v[20:23], v[170:173], v[198:201], v[20:23]
	v_mfma_f32_16x16x32_bf16 v[12:15], v[162:165], v[206:209], v[12:15]
	v_mfma_f32_16x16x32_bf16 v[4:7], v[170:173], v[206:209], v[4:7]
	s_setprio 0
	s_barrier
.La1_ph3:
	s_add_i32 s52, 16, 0x18000
	v_add_u32_e32 v3, s52, v175
	s_add_i32 s53, 16, 0x1c000
	ds_read_b128 v[142:145], v3
	ds_read_b128 v[146:149], v3 offset:1024
	ds_read_b128 v[150:153], v3 offset:2048
	ds_read_b128 v[154:157], v3 offset:3072
	v_add_u32_e32 v3, s53, v175
	ds_read_b128 v[158:161], v3
	ds_read_b128 v[162:165], v3 offset:1024
	ds_read_b128 v[166:169], v3 offset:2048
	ds_read_b128 v[170:173], v3 offset:3072
	s_mov_b32 m0, s39
	s_nop 0
	global_load_lds_dwordx4 v[214:215], off
	s_mov_b32 m0, s40
	s_nop 0
	global_load_lds_dwordx4 v[216:217], off
	s_add_u32 s30, s30, 0x40000
	s_addc_u32 s31, s31, 0
	s_mov_b32 m0, s41
	v_lshl_add_u64 v[218:219], s[30:31], 0, v[136:137]
	ds_read_b128 v[178:181], v177 offset:32768
	ds_read_b128 v[182:185], v177 offset:33792
	ds_read_b128 v[186:189], v177 offset:34816
	ds_read_b128 v[190:193], v177 offset:35840
	ds_read_b128 v[194:197], v177 offset:36864
	ds_read_b128 v[198:201], v177 offset:37888
	ds_read_b128 v[202:205], v177 offset:38912
	ds_read_b128 v[206:209], v177 offset:39936
	global_load_lds_dwordx4 v[218:219], off
	v_lshl_add_u64 v[218:219], s[30:31], 0, v[132:133]
	s_mov_b32 m0, s42
	s_nop 0
	global_load_lds_dwordx4 v[218:219], off
	s_waitcnt vmcnt(8)
	s_waitcnt lgkmcnt(0)
	s_barrier
	s_setprio 1
	s_waitcnt lgkmcnt(0)
	v_mfma_f32_16x16x32_bf16 v[128:131], v[142:145], v[178:181], v[128:131]
	v_mfma_f32_16x16x32_bf16 v[120:123], v[150:153], v[178:181], v[120:123]
	v_mfma_f32_16x16x32_bf16 v[112:115], v[142:145], v[186:189], v[112:115]
	v_mfma_f32_16x16x32_bf16 v[104:107], v[150:153], v[186:189], v[104:107]
	v_mfma_f32_16x16x32_bf16 v[96:99], v[142:145], v[194:197], v[96:99]
	v_mfma_f32_16x16x32_bf16 v[88:91], v[150:153], v[194:197], v[88:91]
	v_mfma_f32_16x16x32_bf16 v[80:83], v[142:145], v[202:205], v[80:83]
	v_mfma_f32_16x16x32_bf16 v[72:75], v[150:153], v[202:205], v[72:75]
	v_mfma_f32_16x16x32_bf16 v[128:131], v[146:149], v[182:185], v[128:131]
	v_mfma_f32_16x16x32_bf16 v[120:123], v[154:157], v[182:185], v[120:123]
	v_mfma_f32_16x16x32_bf16 v[112:115], v[146:149], v[190:193], v[112:115]
	v_mfma_f32_16x16x32_bf16 v[104:107], v[154:157], v[190:193], v[104:107]
	v_mfma_f32_16x16x32_bf16 v[96:99], v[146:149], v[198:201], v[96:99]
	v_mfma_f32_16x16x32_bf16 v[88:91], v[154:157], v[198:201], v[88:91]
	v_mfma_f32_16x16x32_bf16 v[80:83], v[146:149], v[206:209], v[80:83]
	v_mfma_f32_16x16x32_bf16 v[72:75], v[154:157], v[206:209], v[72:75]
	s_setprio 0
	s_setprio 1
	v_mfma_f32_16x16x32_bf16 v[124:127], v[158:161], v[178:181], v[124:127]
	v_mfma_f32_16x16x32_bf16 v[116:119], v[166:169], v[178:181], v[116:119]
	v_mfma_f32_16x16x32_bf16 v[108:111], v[158:161], v[186:189], v[108:111]
	v_mfma_f32_16x16x32_bf16 v[100:103], v[166:169], v[186:189], v[100:103]
	v_mfma_f32_16x16x32_bf16 v[92:95], v[158:161], v[194:197], v[92:95]
	v_mfma_f32_16x16x32_bf16 v[84:87], v[166:169], v[194:197], v[84:87]
	v_mfma_f32_16x16x32_bf16 v[76:79], v[158:161], v[202:205], v[76:79]
	v_mfma_f32_16x16x32_bf16 v[68:71], v[166:169], v[202:205], v[68:71]
	v_mfma_f32_16x16x32_bf16 v[124:127], v[162:165], v[182:185], v[124:127]
	v_mfma_f32_16x16x32_bf16 v[116:119], v[170:173], v[182:185], v[116:119]
	v_mfma_f32_16x16x32_bf16 v[108:111], v[162:165], v[190:193], v[108:111]
	v_mfma_f32_16x16x32_bf16 v[100:103], v[170:173], v[190:193], v[100:103]
	v_mfma_f32_16x16x32_bf16 v[92:95], v[162:165], v[198:201], v[92:95]
	v_mfma_f32_16x16x32_bf16 v[84:87], v[170:173], v[198:201], v[84:87]
	v_mfma_f32_16x16x32_bf16 v[76:79], v[162:165], v[206:209], v[76:79]
	v_mfma_f32_16x16x32_bf16 v[68:71], v[170:173], v[206:209], v[68:71]
	s_setprio 0
	s_barrier
	s_add_i32 s30, s52, s38
	v_lshl_add_u64 v[210:211], v[210:211], 0, s[84:85]
	s_mov_b32 m0, s30
	ds_read_b128 v[178:181], v177 offset:49152
	ds_read_b128 v[182:185], v177 offset:50176
	ds_read_b128 v[186:189], v177 offset:51200
	ds_read_b128 v[190:193], v177 offset:52224
	ds_read_b128 v[194:197], v177 offset:53248
	ds_read_b128 v[198:201], v177 offset:54272
	ds_read_b128 v[202:205], v177 offset:55296
	ds_read_b128 v[206:209], v177 offset:56320
	global_load_lds_dwordx4 v[210:211], off
	s_add_i32 m0, s30, 0x2000
	s_add_u32 s28, s28, 0x40080
	v_lshl_add_u64 v[210:211], v[212:213], 0, s[84:85]
	s_addc_u32 s29, s29, 0
	s_add_i32 s30, s53, s38
	global_load_lds_dwordx4 v[210:211], off
	v_lshl_add_u64 v[210:211], s[28:29], 0, v[134:135]
	s_mov_b32 m0, s30
	s_nop 0
	global_load_lds_dwordx4 v[210:211], off
	v_lshl_add_u64 v[210:211], s[28:29], 0, v[0:1]
	s_add_i32 m0, s30, 0x2000
	s_nop 0
	global_load_lds_dwordx4 v[210:211], off
	v_lshl_add_u64 v[210:211], v[214:215], 0, s[84:85]
	s_mov_b32 m0, s44
	s_nop 0
	global_load_lds_dwordx4 v[210:211], off
	v_lshl_add_u64 v[210:211], v[216:217], 0, s[84:85]
	s_mov_b32 m0, s45
	s_nop 0
	global_load_lds_dwordx4 v[210:211], off
	s_waitcnt vmcnt(8)
	s_waitcnt lgkmcnt(0)
	s_barrier
	s_setprio 1
	s_waitcnt lgkmcnt(0)
	v_mfma_f32_16x16x32_bf16 v[64:67], v[142:145], v[178:181], v[64:67]
	v_mfma_f32_16x16x32_bf16 v[56:59], v[150:153], v[178:181], v[56:59]
	v_mfma_f32_16x16x32_bf16 v[48:51], v[142:145], v[186:189], v[48:51]
	v_mfma_f32_16x16x32_bf16 v[40:43], v[150:153], v[186:189], v[40:43]
	v_mfma_f32_16x16x32_bf16 v[32:35], v[142:145], v[194:197], v[32:35]
	v_mfma_f32_16x16x32_bf16 v[24:27], v[150:153], v[194:197], v[24:27]
	v_mfma_f32_16x16x32_bf16 v[16:19], v[142:145], v[202:205], v[16:19]
	v_mfma_f32_16x16x32_bf16 v[8:11], v[150:153], v[202:205], v[8:11]
	v_mfma_f32_16x16x32_bf16 v[64:67], v[146:149], v[182:185], v[64:67]
	v_mfma_f32_16x16x32_bf16 v[56:59], v[154:157], v[182:185], v[56:59]
	v_mfma_f32_16x16x32_bf16 v[48:51], v[146:149], v[190:193], v[48:51]
	v_mfma_f32_16x16x32_bf16 v[40:43], v[154:157], v[190:193], v[40:43]
	v_mfma_f32_16x16x32_bf16 v[32:35], v[146:149], v[198:201], v[32:35]
	v_mfma_f32_16x16x32_bf16 v[24:27], v[154:157], v[198:201], v[24:27]
	v_mfma_f32_16x16x32_bf16 v[16:19], v[146:149], v[206:209], v[16:19]
	v_mfma_f32_16x16x32_bf16 v[8:11], v[154:157], v[206:209], v[8:11]
	s_setprio 0
	s_setprio 1
	v_mfma_f32_16x16x32_bf16 v[60:63], v[158:161], v[178:181], v[60:63]
	v_mfma_f32_16x16x32_bf16 v[52:55], v[166:169], v[178:181], v[52:55]
	v_mfma_f32_16x16x32_bf16 v[44:47], v[158:161], v[186:189], v[44:47]
	v_mfma_f32_16x16x32_bf16 v[36:39], v[166:169], v[186:189], v[36:39]
	v_mfma_f32_16x16x32_bf16 v[28:31], v[158:161], v[194:197], v[28:31]
	v_mfma_f32_16x16x32_bf16 v[20:23], v[166:169], v[194:197], v[20:23]
	v_mfma_f32_16x16x32_bf16 v[12:15], v[158:161], v[202:205], v[12:15]
	v_mfma_f32_16x16x32_bf16 v[4:7], v[166:169], v[202:205], v[4:7]
	v_mfma_f32_16x16x32_bf16 v[60:63], v[162:165], v[182:185], v[60:63]
	v_mfma_f32_16x16x32_bf16 v[52:55], v[170:173], v[182:185], v[52:55]
	v_mfma_f32_16x16x32_bf16 v[44:47], v[162:165], v[190:193], v[44:47]
	v_mfma_f32_16x16x32_bf16 v[36:39], v[170:173], v[190:193], v[36:39]
	v_mfma_f32_16x16x32_bf16 v[28:31], v[162:165], v[198:201], v[28:31]
	v_mfma_f32_16x16x32_bf16 v[20:23], v[170:173], v[198:201], v[20:23]
	v_mfma_f32_16x16x32_bf16 v[12:15], v[162:165], v[206:209], v[12:15]
	v_mfma_f32_16x16x32_bf16 v[4:7], v[170:173], v[206:209], v[4:7]
	s_setprio 0
	s_add_i32 s51, s51, 2
	s_add_u32 s0, s0, 0x100
	s_addc_u32 s1, s1, 0
	s_add_u32 s49, s49, 0x100
	s_addc_u32 s50, s50, 0
	s_add_u32 s28, s0, 0xfffc0080
	s_addc_u32 s29, s1, -1
	s_cmp_eq_u32 s51, 12
	s_cselect_b32 s31, s3, s29
	s_cselect_b32 s30, s23, s28
	s_cselect_b32 s29, s21, s50
	s_cselect_b32 s28, s48, s49
	s_barrier
	s_cmp_gt_u32 s51, 13
	s_cbranch_scc0 .LBB0_446
	s_and_b64 vcc, exec, s[18:19]
	s_cbranch_vccz .LBB0_449
	s_barrier
